# S5 output stage stagger: waves 0-3 (the prioritised half) delayed by s_sleep 24 instead of waves 4-7
# speedup vs baseline: 1.0008x; 1.0008x over previous
; #define LAS __attribute__((address_space(3)))
; #define S5_LAUNDER() int tid_ = tid0, lane_ = lane0; asm volatile("" : "+v"(tid_), "+v"(lane_)); const int tid = tid_, lane = lane_, fr = lane & 15, fq = lane >> 4; (void)tid; (void)fr; (void)fq
; __device__ __forceinline__ void s5_prompt_item_mfma(LAS unsigned char* lds, int tid0, int lane0, int wave, int n, int g, const bf16* USg, const bf16* FTg, const bf16* WTg, const bf16* GTg, ...
;     ...
;     S5_LAUNDER();
; #pragma unroll
;     for (int it = 0; it < 4; ++it) { const int q = tid + 512 * it; *(LAS v4u*)(lds + R2_OFF + q * 16) = ftq[it]; }
;     const f32x4 dk = *(const f32x4*)(dsk + 4 * fq);
;     __syncthreads();
;     bf16x8 hbv[4][4];
; #pragma unroll
;     for (int kk = 0; kk < 4; ++kk)
; #pragma unroll
;         for (int cb = 0; cb < 4; ++cb) hbv[kk][cb] = *(const LAS bf16x8*)(lds + HP_OFF + (16 * cb + fr) * 272 + 64 * kk + 16 * fq);
.LBB0_852:
	s_or_b64 exec, exec, s[54:55]
	v_mov_b32_e32 v201, v196
	v_mov_b32_e32 v2, v192
	s_lshl_b32 s10, s65, 6
	s_barrier
	s_add_u32 s10, s52, s10
	v_ashrrev_i32_e32 v202, 4, v201
	v_lshlrev_b32_e32 v194, 2, v202
	s_addc_u32 s11, s53, 0
	v_ashrrev_i32_e32 v195, 31, v194
	v_lshl_add_u64 v[20:21], v[194:195], 2, s[10:11]
	global_load_dwordx4 v[20:23], v[20:21], off
	s_add_i32 s10, 0, 0x10800
	v_and_b32_e32 v203, 15, v201
	v_lshl_add_u32 v2, v2, 4, s10
	s_waitcnt vmcnt(20)
	ds_write_b128 v2, v[24:27]
	s_waitcnt vmcnt(19)
	ds_write_b128 v2, v[28:31] offset:8192
	s_waitcnt vmcnt(18)
	ds_write_b128 v2, v[32:35] offset:16384
	s_waitcnt vmcnt(17)
	ds_write_b128 v2, v[36:39] offset:24576
	v_and_b32_e32 v2, -16, v201
	s_add_i32 s11, 0, 0x18c00
	v_mul_u32_u24_e32 v24, 0x110, v203
	v_add3_u32 v2, s11, v2, v24
	s_waitcnt lgkmcnt(0)
	s_barrier
	v_readfirstlane_b32 s99, v192
	s_nop 3
	s_lshr_b32 s99, s99, 6
	s_cmp_ge_u32 s99, 4
	s_cbranch_scc1 .Ls5_stag
	s_sleep 24
